# mixer queue: first item static per CU (K/V-sharing attention items of a group on one XCD, 8 HGRN units per XCD), later items claimed from 256
# baseline (speedup 1.0000x reference)
; DI void phase_mix(const P& p, int l, int rep, char* lds) {
;   __shared__ int s_item;
;   const int nitems = 64 + 512 + 256 + 256 + (l == 0 ? 128 : 0);
;   const float lam_init = (l == 0) ? 0.2f : (0.8f - 0.6f * 0.7408182206817179f);
;   const float* dl = p.df_lam + l * 128;
;   float d01 = 0.f, d23 = 0.f;
;   for (int i = 0; i < 32; ++i) {
;     d01 += dl[i] * dl[32 + i];
;     d23 += dl[64 + i] * dl[96 + i];
;   }
;   const float lam = expf(d01) - expf(d23) + lam_init;
;   const float* subln = p.df_subln + l * 64;
;   const float cB = 0.125f * LOG2E, cC = 0.17677669529663687f * LOG2E;
.LBB0_812:
	s_andn2_b64 vcc, exec, s[0:1]
	s_cbranch_vccnz .LBB0_941
	s_cmp_gt_u32 s23, 3
	s_cselect_b64 s[0:1], -1, 0
	v_writelane_b32 v255, s0, 52
	v_mov_b32_e32 v0, 0x3eb60549
	v_mov_b32_e32 v130, 0x3e4ccccd
	v_writelane_b32 v255, s1, 53
	s_lshl_b32 s0, s50, 7
	s_ashr_i32 s1, s0, 31
	s_lshl_b64 s[0:1], s[0:1], 2
	s_add_u32 s0, s4, s0
	s_addc_u32 s1, s5, s1
	global_load_dwordx4 v[2:5], v1, s[0:1]
	global_load_dwordx4 v[6:9], v1, s[0:1] offset:128
	global_load_dwordx4 v[10:13], v1, s[0:1] offset:256
	global_load_dwordx4 v[14:17], v1, s[0:1] offset:384
	global_load_dwordx4 v[18:21], v1, s[0:1] offset:16
	global_load_dwordx4 v[22:25], v1, s[0:1] offset:144
	global_load_dwordx4 v[26:29], v1, s[0:1] offset:272
	global_load_dwordx4 v[30:33], v1, s[0:1] offset:400
	global_load_dwordx4 v[34:37], v1, s[0:1] offset:32
	global_load_dwordx4 v[38:41], v1, s[0:1] offset:160
	global_load_dwordx4 v[42:45], v1, s[0:1] offset:288
	global_load_dwordx4 v[46:49], v1, s[0:1] offset:416
	global_load_dwordx4 v[50:53], v1, s[0:1] offset:48
	global_load_dwordx4 v[54:57], v1, s[0:1] offset:176
	global_load_dwordx4 v[58:61], v1, s[0:1] offset:304
	global_load_dwordx4 v[62:65], v1, s[0:1] offset:432
	global_load_dwordx4 v[66:69], v1, s[0:1] offset:64
	global_load_dwordx4 v[70:73], v1, s[0:1] offset:192
	global_load_dwordx4 v[74:77], v1, s[0:1] offset:320
	global_load_dwordx4 v[78:81], v1, s[0:1] offset:448
	global_load_dwordx4 v[82:85], v1, s[0:1] offset:80
	global_load_dwordx4 v[86:89], v1, s[0:1] offset:208
	global_load_dwordx4 v[90:93], v1, s[0:1] offset:336
	global_load_dwordx4 v[94:97], v1, s[0:1] offset:464
	global_load_dwordx4 v[98:101], v1, s[0:1] offset:96
	global_load_dwordx4 v[102:105], v1, s[0:1] offset:224
	global_load_dwordx4 v[106:109], v1, s[0:1] offset:352
	global_load_dwordx4 v[110:113], v1, s[0:1] offset:480
	global_load_dwordx4 v[114:117], v1, s[0:1] offset:112
	global_load_dwordx4 v[118:121], v1, s[0:1] offset:240
	global_load_dwordx4 v[122:125], v1, s[0:1] offset:368
	global_load_dwordx4 v[126:129], v1, s[0:1] offset:496
	s_lshl_b32 s0, s50, 6
	s_ashr_i32 s1, s0, 31
	s_lshl_b64 s[0:1], s[0:1], 2
	s_add_u32 s24, s6, s0
	s_addc_u32 s25, s7, s1
	s_ashr_i32 s51, s50, 31
	s_and_b32 s2, s23, -4
	v_writelane_b32 v255, s24, 54
	s_cmp_lt_u32 s23, 4
	s_cselect_b64 vcc, -1, 0
	v_writelane_b32 v255, s25, 55
	v_writelane_b32 v255, s2, 56
	s_and_b64 s[24:25], vcc, exec
	s_movk_i32 s2, 0x4c0
	s_cselect_b32 s59, s2, 0x440
	s_mov_b32 s2, 0x3fb8aa3b
	s_cselect_b32 s25, 0x9000, s21
	s_lshl_b64 s[26:27], s[50:51], 2
	v_readlane_b32 s40, v255, 24
	v_readlane_b32 s41, v255, 25
	s_add_u32 s26, s40, s26
	v_cndmask_b32_e32 v0, v0, v130, vcc
	s_addc_u32 s27, s41, s27
	s_mov_b32 s23, 0x42b17218
	v_writelane_b32 v255, s26, 57
	v_sub_f32_e32 v227, 1.0, v0
	s_waitcnt vmcnt(30)
	v_fma_f32 v2, v2, v6, 0
	v_fmac_f32_e32 v2, v3, v7
	v_fmac_f32_e32 v2, v4, v8
	v_fmac_f32_e32 v2, v5, v9
	s_waitcnt vmcnt(26)
	v_fmac_f32_e32 v2, v18, v22
	v_fmac_f32_e32 v2, v19, v23
	v_fmac_f32_e32 v2, v20, v24
	v_fmac_f32_e32 v2, v21, v25
	v_fma_f32 v6, v10, v14, 0
	s_waitcnt vmcnt(22)
	v_fmac_f32_e32 v2, v34, v38
	v_fmac_f32_e32 v6, v11, v15
	v_fmac_f32_e32 v2, v35, v39
	v_fmac_f32_e32 v6, v12, v16
	v_fmac_f32_e32 v2, v36, v40
	v_fmac_f32_e32 v6, v13, v17
	v_fmac_f32_e32 v2, v37, v41
	v_fmac_f32_e32 v6, v26, v30
	s_waitcnt vmcnt(18)
	v_fmac_f32_e32 v2, v50, v54
	v_fmac_f32_e32 v6, v27, v31
	v_fmac_f32_e32 v2, v51, v55
	v_fmac_f32_e32 v6, v28, v32
	v_fmac_f32_e32 v2, v52, v56
	v_fmac_f32_e32 v6, v29, v33
	v_fmac_f32_e32 v2, v53, v57
	v_fmac_f32_e32 v6, v42, v46
	s_waitcnt vmcnt(14)
	v_fmac_f32_e32 v2, v66, v70
	v_fmac_f32_e32 v6, v43, v47
	v_fmac_f32_e32 v2, v67, v71
	v_fmac_f32_e32 v6, v44, v48
	v_fmac_f32_e32 v2, v68, v72
	v_fmac_f32_e32 v6, v45, v49
	v_fmac_f32_e32 v2, v69, v73
	v_fmac_f32_e32 v6, v58, v62
	s_waitcnt vmcnt(10)
	v_fmac_f32_e32 v2, v82, v86
	v_fmac_f32_e32 v6, v59, v63
	v_fmac_f32_e32 v2, v83, v87
	v_fmac_f32_e32 v6, v60, v64
	v_fmac_f32_e32 v2, v84, v88
	v_fmac_f32_e32 v6, v61, v65
	v_fmac_f32_e32 v2, v85, v89
	v_fmac_f32_e32 v6, v74, v78
	s_waitcnt vmcnt(6)
	v_fmac_f32_e32 v2, v98, v102
	v_fmac_f32_e32 v6, v75, v79
	v_fmac_f32_e32 v2, v99, v103
	v_fmac_f32_e32 v6, v76, v80
	v_fmac_f32_e32 v2, v100, v104
	v_fmac_f32_e32 v6, v77, v81
	v_fmac_f32_e32 v2, v101, v105
	v_fmac_f32_e32 v6, v90, v94
	s_waitcnt vmcnt(2)
	v_fmac_f32_e32 v2, v114, v118
	v_fmac_f32_e32 v6, v91, v95
	v_fmac_f32_e32 v2, v115, v119
	v_fmac_f32_e32 v6, v92, v96
	v_fmac_f32_e32 v2, v116, v120
	v_fmac_f32_e32 v6, v93, v97
	v_fmac_f32_e32 v2, v117, v121
	v_fmac_f32_e32 v6, v106, v110
	v_mul_f32_e32 v3, 0x3fb8aa3b, v2
	v_fmac_f32_e32 v6, v107, v111
	v_fma_f32 v4, v2, s2, -v3
	v_rndne_f32_e32 v5, v3
	v_fmac_f32_e32 v6, v108, v112
	v_fmac_f32_e32 v4, 0x32a5705f, v2
	v_sub_f32_e32 v3, v3, v5
	v_fmac_f32_e32 v6, v109, v113
	v_add_f32_e32 v3, v3, v4
	s_waitcnt vmcnt(0)
	v_fmac_f32_e32 v6, v122, v126
	v_exp_f32_e32 v3, v3
	v_cvt_i32_f32_e32 v4, v5
	v_fmac_f32_e32 v6, v123, v127
	v_fmac_f32_e32 v6, v124, v128
	v_fmac_f32_e32 v6, v125, v129
	v_ldexp_f32 v3, v3, v4
	v_mul_f32_e32 v4, 0x3fb8aa3b, v6
	v_fma_f32 v5, v6, s2, -v4
	v_rndne_f32_e32 v7, v4
	v_fmac_f32_e32 v5, 0x32a5705f, v6
	v_sub_f32_e32 v4, v4, v7
	v_add_f32_e32 v4, v4, v5
	v_exp_f32_e32 v4, v4
	v_cvt_i32_f32_e32 v5, v7
	s_mov_b32 s2, 0xc2ce8ed0
	v_cmp_ngt_f32_e32 vcc, s2, v2
	v_mov_b32_e32 v7, 0x7f800000
	v_writelane_b32 v255, s27, 58
	v_cndmask_b32_e32 v3, 0, v3, vcc
	v_cmp_nlt_f32_e32 vcc, s23, v2
	v_readlane_b32 s44, v255, 36
	v_readlane_b32 s50, v255, 42
	v_cndmask_b32_e32 v2, v7, v3, vcc
	v_ldexp_f32 v3, v4, v5
	v_cmp_ngt_f32_e32 vcc, s2, v6
	v_readlane_b32 s51, v255, 43
	s_add_u32 s0, s50, s0
	v_cndmask_b32_e32 v3, 0, v3, vcc
	v_cmp_nlt_f32_e32 vcc, s23, v6
	v_readlane_b32 s45, v255, 37
	v_readlane_b32 s46, v255, 38
	v_cndmask_b32_e32 v3, v7, v3, vcc
	v_sub_f32_e32 v2, v2, v3
	v_readlane_b32 s47, v255, 39
	v_readlane_b32 s48, v255, 40
	v_readlane_b32 s49, v255, 41
	s_addc_u32 s1, s51, s1
	v_add_f32_e32 v228, v0, v2
	v_writelane_b32 v255, s59, 59
	s_mov_b32 s100, 1
	s_branch .LBB0_817

; DI int tidx() { int t = threadIdx.x; asm volatile("" : "+v"(t)); return t; }
; DI void phase_mix(const P& p, int l, int rep, char* lds) {
;     ...
;   while (true) {
;     if (tidx() == 0) s_item = atomicAdd(&p.ctr[l + 2 * rep], 1);
;     __syncthreads();
;     int it = __builtin_amdgcn_readfirstlane(s_item);
;     __syncthreads();
;     if (it >= nitems) break;
;     if (it < 64) {
;       hgrn_unit(p, l, it, lds);
;       continue;
;     }
.LBB0_817:
	s_cmp_eq_u32 s100, 0
	s_cbranch_scc1 .Lmix_claim
	s_mov_b32 s100, 0
	v_readlane_b32 s26, v254, 0
	s_and_b32 s2, s26, 7
	s_lshr_b32 s26, s26, 3
	s_cmp_lt_u32 s26, 24
	s_cbranch_scc0 .Lmix_first_hgrn
	s_mul_i32 s2, s2, 24
	s_add_i32 s26, s26, s2
	s_addk_i32 s26, 64
	s_branch .Lmix_first_done
.Lmix_first_hgrn:
	s_lshl_b32 s2, s2, 3
	s_add_i32 s26, s26, s2
	s_addk_i32 s26, 0xffe8
.Lmix_first_done:
	s_mov_b64 s[40:41], -1
	s_branch .Lmix_have_item

; DI int tidx() { int t = threadIdx.x; asm volatile("" : "+v"(t)); return t; }
; DI void phase_mix(const P& p, int l, int rep, char* lds) {
;     ...
;     if (tidx() == 0) s_item = atomicAdd(&p.ctr[l + 2 * rep], 1);
;     __syncthreads();
;     int it = __builtin_amdgcn_readfirstlane(s_item);
;     __syncthreads();
;     if (it >= nitems) break;
;     if (it < 64) {
;       hgrn_unit(p, l, it, lds);
;       continue;
;     }
;     it -= 64;
;     int mode, b, hq, qb, sq0, sq1, sk, sv, qtok0, ka0, na, kb0 = 2048, nb = 0, yrow0, ycol0;
;     bool window = false, has_sink = false, isctx = false;
;     int kind;
;     if (it < 512) { kind = 0; b = it >> 5; hq = (it >> 3) & 3; qb = it & 7; }
;     else if (it < 768) { it -= 512; kind = 1; b = it >> 4; hq = (it >> 3) & 1; qb = it & 7; }
;     else if (it < 1024) { it -= 768; kind = 2; b = it >> 4; hq = (it >> 3) & 1; qb = it & 7; }
;     else if (it < 1088) { it -= 1024; kind = 0; isctx = true; b = it >> 2; hq = it & 3; qb = 0; }
;     else if (it < 1120) { it -= 1088; kind = 1; isctx = true; b = it >> 1; hq = it & 1; qb = 0; }
;     else { it -= 1120; kind = 2; isctx = true; b = it >> 1; hq = it & 1; qb = 0; }
.LBB0_821:
	s_or_b64 exec, exec, s[40:41]
	s_waitcnt lgkmcnt(0)
	s_barrier
	ds_read_b32 v0, v1 offset:16
	s_mov_b64 s[40:41], -1
	s_waitcnt lgkmcnt(0)
	s_barrier
	v_readfirstlane_b32 s26, v0
	s_addk_i32 s26, 0x100
.Lmix_have_item:
	s_cmp_ge_i32 s26, s59
	s_cbranch_scc1 .LBB0_816
	s_cmp_gt_i32 s26, 63
	s_cbranch_scc0 .LBB0_899
	s_cmpk_gt_u32 s26, 0x23f
	s_mov_b64 s[44:45], -1
	s_cbranch_scc0 .LBB0_840
	s_cmpk_gt_u32 s26, 0x33f
	s_cbranch_scc0 .LBB0_837
	s_mov_b64 s[46:47], -1
	s_cmpk_gt_u32 s26, 0x43f
	s_cbranch_scc0 .LBB0_834
	s_cmpk_gt_u32 s26, 0x47f
	s_mov_b64 s[40:41], -1
	s_cbranch_scc0 .LBB0_832
	s_cmpk_gt_u32 s26, 0x49f
	s_mov_b64 s[42:43], -1
	s_cbranch_scc0 .LBB0_829
	s_add_i32 s2, s26, 0xfffffb60
	s_lshr_b32 s2, s2, 1
	s_mov_b64 s[44:45], 0
